# v100 + non-leader workgroups poll the top-level generation word directly (every XCD leader has finished writeback + invalidate before its top-level arrival, so the per-XCD relay hop is not needed)
# speedup vs baseline: 1.0042x; 1.0042x over previous
.LBB0_29:
	s_or_b64 exec, exec, s[14:15]
	v_cvt_f32_u32_e32 v5, v3
	s_waitcnt vmcnt(0)
	v_readfirstlane_b32 s11, v4
	v_sub_u32_e32 v4, 0, v3
	v_rcp_iflag_f32_e32 v5, v5
	v_add_u32_e32 v6, s11, v2
	v_mul_f32_e32 v5, 0x4f7ffffe, v5
	v_cvt_u32_f32_e32 v5, v5
	v_mul_lo_u32 v2, v4, v5
	v_mul_hi_u32 v2, v5, v2
	v_add_u32_e32 v2, v5, v2
	v_mul_hi_u32 v2, v6, v2
	v_mul_lo_u32 v4, v2, v3
	v_sub_u32_e32 v4, v6, v4
	v_add_u32_e32 v5, 1, v2
	v_cmp_ge_u32_e32 vcc, v4, v3
	s_nop 1
	v_cndmask_b32_e32 v2, v2, v5, vcc
	v_sub_u32_e32 v5, v4, v3
	v_cndmask_b32_e32 v4, v4, v5, vcc
	v_add_u32_e32 v5, 1, v2
	v_cmp_ge_u32_e32 vcc, v4, v3
	v_add_u32_e32 v4, 1, v6
	s_nop 0
	v_cndmask_b32_e32 v2, v2, v5, vcc
	v_mul_lo_u32 v5, v3, v2
	v_add_u32_e32 v3, v5, v3
	v_cmp_ne_u32_e32 vcc, v4, v3
	s_and_saveexec_b64 s[12:13], vcc
	s_xor_b64 s[12:13], exec, s[12:13]
	s_cbranch_execz .LBB0_43
	s_waitcnt lgkmcnt(0)
	buffer_inv sc1
	v_mov_b32_e32 v1, 0x3000
	global_load_dword v1, v1, s[4:5] offset:1280 sc1
	s_add_u32 s20, s4, 0x3500
	s_addc_u32 s21, s5, 0
	s_waitcnt vmcnt(0)
	v_cmp_eq_u32_e32 vcc, v1, v2
	s_and_saveexec_b64 s[14:15], vcc
	s_cbranch_execz .LBB0_42
	s_mov_b32 s11, 1
	s_mov_b64 s[22:23], 0
	v_mov_b32_e32 v1, 0
	s_branch .LBB0_33

.LBB0_181:
	s_or_b64 exec, exec, s[14:15]
	v_cvt_f32_u32_e32 v5, v3
	s_waitcnt vmcnt(0)
	v_readfirstlane_b32 s11, v4
	v_sub_u32_e32 v4, 0, v3
	v_rcp_iflag_f32_e32 v5, v5
	v_add_u32_e32 v6, s11, v2
	v_mul_f32_e32 v5, 0x4f7ffffe, v5
	v_cvt_u32_f32_e32 v5, v5
	v_mul_lo_u32 v2, v4, v5
	v_mul_hi_u32 v2, v5, v2
	v_add_u32_e32 v2, v5, v2
	v_mul_hi_u32 v2, v6, v2
	v_mul_lo_u32 v4, v2, v3
	v_sub_u32_e32 v4, v6, v4
	v_add_u32_e32 v5, 1, v2
	v_cmp_ge_u32_e32 vcc, v4, v3
	s_nop 1
	v_cndmask_b32_e32 v2, v2, v5, vcc
	v_sub_u32_e32 v5, v4, v3
	v_cndmask_b32_e32 v4, v4, v5, vcc
	v_add_u32_e32 v5, 1, v2
	v_cmp_ge_u32_e32 vcc, v4, v3
	v_add_u32_e32 v4, 1, v6
	s_nop 0
	v_cndmask_b32_e32 v2, v2, v5, vcc
	v_mul_lo_u32 v5, v3, v2
	v_add_u32_e32 v3, v5, v3
	v_cmp_ne_u32_e32 vcc, v4, v3
	s_and_saveexec_b64 s[12:13], vcc
	s_xor_b64 s[12:13], exec, s[12:13]
	s_cbranch_execz .LBB0_195
	s_waitcnt lgkmcnt(0)
	buffer_inv sc1
	v_mov_b32_e32 v1, 0x3000
	global_load_dword v1, v1, s[6:7] offset:1280 sc1
	s_add_u32 s20, s6, 0x3500
	s_addc_u32 s21, s7, 0
	s_waitcnt vmcnt(0)
	v_cmp_eq_u32_e32 vcc, v1, v2
	s_and_saveexec_b64 s[14:15], vcc
	s_cbranch_execz .LBB0_194
	s_mov_b32 s11, 1
	s_mov_b64 s[22:23], 0
	v_mov_b32_e32 v1, 0
	s_branch .LBB0_185

.LBB0_383:
	s_or_b64 exec, exec, s[12:13]
	v_cvt_f32_u32_e32 v5, v3
	s_waitcnt vmcnt(0)
	v_readfirstlane_b32 s8, v4
	v_sub_u32_e32 v4, 0, v3
	v_rcp_iflag_f32_e32 v5, v5
	v_add_u32_e32 v6, s8, v2
	v_mul_f32_e32 v5, 0x4f7ffffe, v5
	v_cvt_u32_f32_e32 v5, v5
	v_mul_lo_u32 v2, v4, v5
	v_mul_hi_u32 v2, v5, v2
	v_add_u32_e32 v2, v5, v2
	v_mul_hi_u32 v2, v6, v2
	v_mul_lo_u32 v4, v2, v3
	v_sub_u32_e32 v4, v6, v4
	v_add_u32_e32 v5, 1, v2
	v_cmp_ge_u32_e32 vcc, v4, v3
	s_nop 1
	v_cndmask_b32_e32 v2, v2, v5, vcc
	v_sub_u32_e32 v5, v4, v3
	v_cndmask_b32_e32 v4, v4, v5, vcc
	v_add_u32_e32 v5, 1, v2
	v_cmp_ge_u32_e32 vcc, v4, v3
	v_add_u32_e32 v4, 1, v6
	s_nop 0
	v_cndmask_b32_e32 v2, v2, v5, vcc
	v_mul_lo_u32 v5, v3, v2
	v_add_u32_e32 v3, v5, v3
	v_cmp_ne_u32_e32 vcc, v4, v3
	s_and_saveexec_b64 s[8:9], vcc
	s_xor_b64 s[8:9], exec, s[8:9]
	s_cbranch_execz .LBB0_397
	s_waitcnt lgkmcnt(0)
	buffer_inv sc1
	v_mov_b32_e32 v1, 0x3000
	global_load_dword v1, v1, s[4:5] offset:1280 sc1
	s_add_u32 s14, s4, 0x3500
	s_addc_u32 s15, s5, 0
	s_waitcnt vmcnt(0)
	v_cmp_eq_u32_e32 vcc, v1, v2
	s_and_saveexec_b64 s[12:13], vcc
	s_cbranch_execz .LBB0_396
	s_mov_b32 s11, 1
	s_mov_b64 s[22:23], 0
	v_mov_b32_e32 v1, 0
	s_branch .LBB0_387

.LBB0_1042:
	s_or_b64 exec, exec, s[14:15]
	v_cvt_f32_u32_e32 v5, v3
	s_waitcnt vmcnt(0)
	v_readfirstlane_b32 s8, v4
	v_sub_u32_e32 v4, 0, v3
	v_rcp_iflag_f32_e32 v5, v5
	v_add_u32_e32 v6, s8, v2
	v_mul_f32_e32 v5, 0x4f7ffffe, v5
	v_cvt_u32_f32_e32 v5, v5
	v_mul_lo_u32 v2, v4, v5
	v_mul_hi_u32 v2, v5, v2
	v_add_u32_e32 v2, v5, v2
	v_mul_hi_u32 v2, v6, v2
	v_mul_lo_u32 v4, v2, v3
	v_sub_u32_e32 v4, v6, v4
	v_add_u32_e32 v5, 1, v2
	v_cmp_ge_u32_e32 vcc, v4, v3
	s_nop 1
	v_cndmask_b32_e32 v2, v2, v5, vcc
	v_sub_u32_e32 v5, v4, v3
	v_cndmask_b32_e32 v4, v4, v5, vcc
	v_add_u32_e32 v5, 1, v2
	v_cmp_ge_u32_e32 vcc, v4, v3
	v_add_u32_e32 v4, 1, v6
	s_nop 0
	v_cndmask_b32_e32 v2, v2, v5, vcc
	v_mul_lo_u32 v5, v3, v2
	v_add_u32_e32 v3, v5, v3
	v_cmp_ne_u32_e32 vcc, v4, v3
	s_and_saveexec_b64 s[8:9], vcc
	s_xor_b64 s[8:9], exec, s[8:9]
	s_cbranch_execz .LBB0_1056
	s_waitcnt lgkmcnt(0)
	buffer_inv sc1
	v_mov_b32_e32 v1, 0x3000
	global_load_dword v1, v1, s[4:5] offset:1280 sc1
	s_add_u32 s20, s4, 0x3500
	s_addc_u32 s21, s5, 0
	s_waitcnt vmcnt(0)
	v_cmp_eq_u32_e32 vcc, v1, v2
	s_and_saveexec_b64 s[14:15], vcc
	s_cbranch_execz .LBB0_1055
	s_mov_b32 s11, 1
	s_mov_b64 s[22:23], 0
	v_mov_b32_e32 v1, 0
	s_branch .LBB0_1046

.LBB0_2506:
	s_or_b64 exec, exec, s[12:13]
	v_cvt_f32_u32_e32 v5, v3
	s_waitcnt vmcnt(0)
	v_readfirstlane_b32 s8, v4
	v_sub_u32_e32 v4, 0, v3
	v_rcp_iflag_f32_e32 v5, v5
	v_add_u32_e32 v6, s8, v2
	v_mul_f32_e32 v5, 0x4f7ffffe, v5
	v_cvt_u32_f32_e32 v5, v5
	v_mul_lo_u32 v2, v4, v5
	v_mul_hi_u32 v2, v5, v2
	v_add_u32_e32 v2, v5, v2
	v_mul_hi_u32 v2, v6, v2
	v_mul_lo_u32 v4, v2, v3
	v_sub_u32_e32 v4, v6, v4
	v_add_u32_e32 v5, 1, v2
	v_cmp_ge_u32_e32 vcc, v4, v3
	s_nop 1
	v_cndmask_b32_e32 v2, v2, v5, vcc
	v_sub_u32_e32 v5, v4, v3
	v_cndmask_b32_e32 v4, v4, v5, vcc
	v_add_u32_e32 v5, 1, v2
	v_cmp_ge_u32_e32 vcc, v4, v3
	v_add_u32_e32 v4, 1, v6
	s_nop 0
	v_cndmask_b32_e32 v2, v2, v5, vcc
	v_mul_lo_u32 v5, v3, v2
	v_add_u32_e32 v3, v5, v3
	v_cmp_ne_u32_e32 vcc, v4, v3
	s_and_saveexec_b64 s[8:9], vcc
	s_xor_b64 s[8:9], exec, s[8:9]
	s_cbranch_execz .LBB0_2520
	s_waitcnt lgkmcnt(0)
	buffer_inv sc1
	v_mov_b32_e32 v1, 0x3000
	global_load_dword v1, v1, s[4:5] offset:1280 sc1
	s_add_u32 s14, s4, 0x3500
	s_addc_u32 s15, s5, 0
	s_waitcnt vmcnt(0)
	v_cmp_eq_u32_e32 vcc, v1, v2
	s_and_saveexec_b64 s[12:13], vcc
	s_cbranch_execz .LBB0_2519
	s_mov_b32 s11, 1
	s_mov_b64 s[18:19], 0
	v_mov_b32_e32 v1, 0
	s_branch .LBB0_2510
